# P6 SwiGLU epilogue: (1+e)*(meansq+eps) by one packed fma feeds rcp, so the separate +1 and *s^2 passes disappear (12 packed ops per row after the up-front gate*up)
# baseline (speedup 1.0000x reference)
.LBB0_674:
	s_andn2_b64 vcc, exec, s[0:1]
	s_mov_b64 s[0:1], -1
	s_waitcnt vmcnt(14)
	v_add_f32_e32 v156, v156, v157
	v_add_f32_e32 v158, v158, v159
	v_add_f32_e32 v160, v160, v161
	v_add_f32_e32 v162, v162, v163
	v_add_f32_e32 v156, v156, v158
	v_add_f32_e32 v160, v160, v162
	v_add_f32_e32 v156, v156, v160
	v_fmamk_f32 v254, v156, 0x3a000000, v154
	v_rsq_f32_e32 v146, v254
	v_mov_b32_e32 v147, v155
	v_mul_f32_e32 v255, v146, v252
	v_pk_mul_f32 v[156:157], v[116:117], v[254:255] op_sel:[0,1]
	v_pk_mul_f32 v[158:159], v[118:119], v[254:255] op_sel:[0,1]
	v_pk_mul_f32 v[160:161], v[112:113], v[254:255] op_sel:[0,1]
	v_pk_mul_f32 v[162:163], v[114:115], v[254:255] op_sel:[0,1]
	v_exp_f32_e32 v156, v156
	v_exp_f32_e32 v157, v157
	v_exp_f32_e32 v158, v158
	v_exp_f32_e32 v159, v159
	v_exp_f32_e32 v160, v160
	v_exp_f32_e32 v161, v161
	v_exp_f32_e32 v162, v162
	v_exp_f32_e32 v163, v163
	v_pk_fma_f32 v[156:157], v[156:157], v[254:255], v[254:255] op_sel_hi:[1,0,0]
	v_pk_fma_f32 v[158:159], v[158:159], v[254:255], v[254:255] op_sel_hi:[1,0,0]
	v_pk_fma_f32 v[160:161], v[160:161], v[254:255], v[254:255] op_sel_hi:[1,0,0]
	v_pk_fma_f32 v[162:163], v[162:163], v[254:255], v[254:255] op_sel_hi:[1,0,0]
	v_rcp_f32_e32 v156, v156
	v_rcp_f32_e32 v157, v157
	v_rcp_f32_e32 v158, v158
	v_rcp_f32_e32 v159, v159
	v_rcp_f32_e32 v160, v160
	v_rcp_f32_e32 v161, v161
	v_rcp_f32_e32 v162, v162
	v_rcp_f32_e32 v163, v163
	v_pk_mul_f32 v[124:125], v[124:125], v[156:157]
	v_pk_mul_f32 v[126:127], v[126:127], v[158:159]
	v_pk_mul_f32 v[120:121], v[120:121], v[160:161]
	v_pk_mul_f32 v[122:123], v[122:123], v[162:163]
	v_cvt_pk_bf16_f32 v112, v124, v125
	v_cvt_pk_bf16_f32 v113, v126, v127
	v_cvt_pk_bf16_f32 v114, v120, v121
	v_cvt_pk_bf16_f32 v115, v122, v123
	global_store_dwordx4 v147, v[112:115], s[8:9]
	s_waitcnt vmcnt(13)
	v_add_f32_e32 v164, v164, v165
	v_add_f32_e32 v166, v166, v167
	v_add_f32_e32 v168, v168, v169
	v_add_f32_e32 v170, v170, v171
	v_add_f32_e32 v164, v164, v166
	v_add_f32_e32 v168, v168, v170
	v_add_f32_e32 v164, v164, v168
	v_fmamk_f32 v254, v164, 0x3a000000, v154
	v_rsq_f32_e32 v146, v254
	v_add_u32_e32 v147, 0x2c000, v155
	v_mul_f32_e32 v255, v146, v252
	v_pk_mul_f32 v[164:165], v[100:101], v[254:255] op_sel:[0,1]
	v_pk_mul_f32 v[166:167], v[102:103], v[254:255] op_sel:[0,1]
	v_pk_mul_f32 v[168:169], v[96:97], v[254:255] op_sel:[0,1]
	v_pk_mul_f32 v[170:171], v[98:99], v[254:255] op_sel:[0,1]
	v_exp_f32_e32 v164, v164
	v_exp_f32_e32 v165, v165
	v_exp_f32_e32 v166, v166
	v_exp_f32_e32 v167, v167
	v_exp_f32_e32 v168, v168
	v_exp_f32_e32 v169, v169
	v_exp_f32_e32 v170, v170
	v_exp_f32_e32 v171, v171
	v_pk_fma_f32 v[164:165], v[164:165], v[254:255], v[254:255] op_sel_hi:[1,0,0]
	v_pk_fma_f32 v[166:167], v[166:167], v[254:255], v[254:255] op_sel_hi:[1,0,0]
	v_pk_fma_f32 v[168:169], v[168:169], v[254:255], v[254:255] op_sel_hi:[1,0,0]
	v_pk_fma_f32 v[170:171], v[170:171], v[254:255], v[254:255] op_sel_hi:[1,0,0]
	v_rcp_f32_e32 v164, v164
	v_rcp_f32_e32 v165, v165
	v_rcp_f32_e32 v166, v166
	v_rcp_f32_e32 v167, v167
	v_rcp_f32_e32 v168, v168
	v_rcp_f32_e32 v169, v169
	v_rcp_f32_e32 v170, v170
	v_rcp_f32_e32 v171, v171
	v_pk_mul_f32 v[108:109], v[108:109], v[164:165]
	v_pk_mul_f32 v[110:111], v[110:111], v[166:167]
	v_pk_mul_f32 v[104:105], v[104:105], v[168:169]
	v_pk_mul_f32 v[106:107], v[106:107], v[170:171]
	v_cvt_pk_bf16_f32 v96, v108, v109
	v_cvt_pk_bf16_f32 v97, v110, v111
	v_cvt_pk_bf16_f32 v98, v104, v105
	v_cvt_pk_bf16_f32 v99, v106, v107
	global_store_dwordx4 v147, v[96:99], s[8:9]
	s_waitcnt vmcnt(12)
	v_add_f32_e32 v172, v172, v173
	v_add_f32_e32 v174, v174, v175
	v_add_f32_e32 v176, v176, v177
	v_add_f32_e32 v178, v178, v179
	v_add_f32_e32 v172, v172, v174
	v_add_f32_e32 v176, v176, v178
	v_add_f32_e32 v172, v172, v176
	v_fmamk_f32 v254, v172, 0x3a000000, v154
	v_rsq_f32_e32 v146, v254
	v_add_u32_e32 v147, 0x58000, v155
	v_mul_f32_e32 v255, v146, v252
	v_pk_mul_f32 v[172:173], v[84:85], v[254:255] op_sel:[0,1]
	v_pk_mul_f32 v[174:175], v[86:87], v[254:255] op_sel:[0,1]
	v_pk_mul_f32 v[176:177], v[80:81], v[254:255] op_sel:[0,1]
	v_pk_mul_f32 v[178:179], v[82:83], v[254:255] op_sel:[0,1]
	v_exp_f32_e32 v172, v172
	v_exp_f32_e32 v173, v173
	v_exp_f32_e32 v174, v174
	v_exp_f32_e32 v175, v175
	v_exp_f32_e32 v176, v176
	v_exp_f32_e32 v177, v177
	v_exp_f32_e32 v178, v178
	v_exp_f32_e32 v179, v179
	v_pk_fma_f32 v[172:173], v[172:173], v[254:255], v[254:255] op_sel_hi:[1,0,0]
	v_pk_fma_f32 v[174:175], v[174:175], v[254:255], v[254:255] op_sel_hi:[1,0,0]
	v_pk_fma_f32 v[176:177], v[176:177], v[254:255], v[254:255] op_sel_hi:[1,0,0]
	v_pk_fma_f32 v[178:179], v[178:179], v[254:255], v[254:255] op_sel_hi:[1,0,0]
	v_rcp_f32_e32 v172, v172
	v_rcp_f32_e32 v173, v173
	v_rcp_f32_e32 v174, v174
	v_rcp_f32_e32 v175, v175
	v_rcp_f32_e32 v176, v176
	v_rcp_f32_e32 v177, v177
	v_rcp_f32_e32 v178, v178
	v_rcp_f32_e32 v179, v179
	v_pk_mul_f32 v[92:93], v[92:93], v[172:173]
	v_pk_mul_f32 v[94:95], v[94:95], v[174:175]
	v_pk_mul_f32 v[88:89], v[88:89], v[176:177]
	v_pk_mul_f32 v[90:91], v[90:91], v[178:179]
	v_cvt_pk_bf16_f32 v80, v92, v93
	v_cvt_pk_bf16_f32 v81, v94, v95
	v_cvt_pk_bf16_f32 v82, v88, v89
	v_cvt_pk_bf16_f32 v83, v90, v91
	global_store_dwordx4 v147, v[80:83], s[8:9]
	s_waitcnt vmcnt(11)
	v_add_f32_e32 v180, v180, v181
	v_add_f32_e32 v182, v182, v183
	v_add_f32_e32 v184, v184, v185
	v_add_f32_e32 v186, v186, v187
	v_add_f32_e32 v180, v180, v182
	v_add_f32_e32 v184, v184, v186
	v_add_f32_e32 v180, v180, v184
	v_fmamk_f32 v254, v180, 0x3a000000, v154
	v_rsq_f32_e32 v146, v254
	v_add_u32_e32 v147, 0x84000, v155
	v_mul_f32_e32 v255, v146, v252
	v_pk_mul_f32 v[180:181], v[68:69], v[254:255] op_sel:[0,1]
	v_pk_mul_f32 v[182:183], v[70:71], v[254:255] op_sel:[0,1]
	v_pk_mul_f32 v[184:185], v[64:65], v[254:255] op_sel:[0,1]
	v_pk_mul_f32 v[186:187], v[66:67], v[254:255] op_sel:[0,1]
	v_exp_f32_e32 v180, v180
	v_exp_f32_e32 v181, v181
	v_exp_f32_e32 v182, v182
	v_exp_f32_e32 v183, v183
	v_exp_f32_e32 v184, v184
	v_exp_f32_e32 v185, v185
	v_exp_f32_e32 v186, v186
	v_exp_f32_e32 v187, v187
	v_pk_fma_f32 v[180:181], v[180:181], v[254:255], v[254:255] op_sel_hi:[1,0,0]
	v_pk_fma_f32 v[182:183], v[182:183], v[254:255], v[254:255] op_sel_hi:[1,0,0]
	v_pk_fma_f32 v[184:185], v[184:185], v[254:255], v[254:255] op_sel_hi:[1,0,0]
	v_pk_fma_f32 v[186:187], v[186:187], v[254:255], v[254:255] op_sel_hi:[1,0,0]
	v_rcp_f32_e32 v180, v180
	v_rcp_f32_e32 v181, v181
	v_rcp_f32_e32 v182, v182
	v_rcp_f32_e32 v183, v183
	v_rcp_f32_e32 v184, v184
	v_rcp_f32_e32 v185, v185
	v_rcp_f32_e32 v186, v186
	v_rcp_f32_e32 v187, v187
	v_pk_mul_f32 v[76:77], v[76:77], v[180:181]
	v_pk_mul_f32 v[78:79], v[78:79], v[182:183]
	v_pk_mul_f32 v[72:73], v[72:73], v[184:185]
	v_pk_mul_f32 v[74:75], v[74:75], v[186:187]
	v_cvt_pk_bf16_f32 v64, v76, v77
	v_cvt_pk_bf16_f32 v65, v78, v79
	v_cvt_pk_bf16_f32 v66, v72, v73
	v_cvt_pk_bf16_f32 v67, v74, v75
	global_store_dwordx4 v147, v[64:67], s[8:9]
	s_waitcnt vmcnt(10)
	v_add_f32_e32 v188, v188, v189
	v_add_f32_e32 v190, v190, v191
	v_add_f32_e32 v192, v192, v193
	v_add_f32_e32 v194, v194, v195
	v_add_f32_e32 v188, v188, v190
	v_add_f32_e32 v192, v192, v194
	v_add_f32_e32 v188, v188, v192
	v_fmamk_f32 v254, v188, 0x3a000000, v154
	v_rsq_f32_e32 v146, v254
	v_add_u32_e32 v147, 0x160000, v155
	v_mul_f32_e32 v255, v146, v252
	v_pk_mul_f32 v[188:189], v[52:53], v[254:255] op_sel:[0,1]
	v_pk_mul_f32 v[190:191], v[54:55], v[254:255] op_sel:[0,1]
	v_pk_mul_f32 v[192:193], v[48:49], v[254:255] op_sel:[0,1]
	v_pk_mul_f32 v[194:195], v[50:51], v[254:255] op_sel:[0,1]
	v_exp_f32_e32 v188, v188
	v_exp_f32_e32 v189, v189
	v_exp_f32_e32 v190, v190
	v_exp_f32_e32 v191, v191
	v_exp_f32_e32 v192, v192
	v_exp_f32_e32 v193, v193
	v_exp_f32_e32 v194, v194
	v_exp_f32_e32 v195, v195
	v_pk_fma_f32 v[188:189], v[188:189], v[254:255], v[254:255] op_sel_hi:[1,0,0]
	v_pk_fma_f32 v[190:191], v[190:191], v[254:255], v[254:255] op_sel_hi:[1,0,0]
	v_pk_fma_f32 v[192:193], v[192:193], v[254:255], v[254:255] op_sel_hi:[1,0,0]
	v_pk_fma_f32 v[194:195], v[194:195], v[254:255], v[254:255] op_sel_hi:[1,0,0]
	v_rcp_f32_e32 v188, v188
	v_rcp_f32_e32 v189, v189
	v_rcp_f32_e32 v190, v190
	v_rcp_f32_e32 v191, v191
	v_rcp_f32_e32 v192, v192
	v_rcp_f32_e32 v193, v193
	v_rcp_f32_e32 v194, v194
	v_rcp_f32_e32 v195, v195
	v_pk_mul_f32 v[60:61], v[60:61], v[188:189]
	v_pk_mul_f32 v[62:63], v[62:63], v[190:191]
	v_pk_mul_f32 v[56:57], v[56:57], v[192:193]
	v_pk_mul_f32 v[58:59], v[58:59], v[194:195]
	v_cvt_pk_bf16_f32 v48, v60, v61
	v_cvt_pk_bf16_f32 v49, v62, v63
	v_cvt_pk_bf16_f32 v50, v56, v57
	v_cvt_pk_bf16_f32 v51, v58, v59
	global_store_dwordx4 v147, v[48:51], s[8:9]
	s_waitcnt vmcnt(9)
	v_add_f32_e32 v196, v196, v197
	v_add_f32_e32 v198, v198, v199
	v_add_f32_e32 v200, v200, v201
	v_add_f32_e32 v202, v202, v203
	v_add_f32_e32 v196, v196, v198
	v_add_f32_e32 v200, v200, v202
	v_add_f32_e32 v196, v196, v200
	v_fmamk_f32 v254, v196, 0x3a000000, v154
	v_rsq_f32_e32 v146, v254
	v_add_u32_e32 v147, 0x18c000, v155
	v_mul_f32_e32 v255, v146, v252
	v_pk_mul_f32 v[196:197], v[36:37], v[254:255] op_sel:[0,1]
	v_pk_mul_f32 v[198:199], v[38:39], v[254:255] op_sel:[0,1]
	v_pk_mul_f32 v[200:201], v[32:33], v[254:255] op_sel:[0,1]
	v_pk_mul_f32 v[202:203], v[34:35], v[254:255] op_sel:[0,1]
	v_exp_f32_e32 v196, v196
	v_exp_f32_e32 v197, v197
	v_exp_f32_e32 v198, v198
	v_exp_f32_e32 v199, v199
	v_exp_f32_e32 v200, v200
	v_exp_f32_e32 v201, v201
	v_exp_f32_e32 v202, v202
	v_exp_f32_e32 v203, v203
	v_pk_fma_f32 v[196:197], v[196:197], v[254:255], v[254:255] op_sel_hi:[1,0,0]
	v_pk_fma_f32 v[198:199], v[198:199], v[254:255], v[254:255] op_sel_hi:[1,0,0]
	v_pk_fma_f32 v[200:201], v[200:201], v[254:255], v[254:255] op_sel_hi:[1,0,0]
	v_pk_fma_f32 v[202:203], v[202:203], v[254:255], v[254:255] op_sel_hi:[1,0,0]
	v_rcp_f32_e32 v196, v196
	v_rcp_f32_e32 v197, v197
	v_rcp_f32_e32 v198, v198
	v_rcp_f32_e32 v199, v199
	v_rcp_f32_e32 v200, v200
	v_rcp_f32_e32 v201, v201
	v_rcp_f32_e32 v202, v202
	v_rcp_f32_e32 v203, v203
	v_pk_mul_f32 v[44:45], v[44:45], v[196:197]
	v_pk_mul_f32 v[46:47], v[46:47], v[198:199]
	v_pk_mul_f32 v[40:41], v[40:41], v[200:201]
	v_pk_mul_f32 v[42:43], v[42:43], v[202:203]
	v_cvt_pk_bf16_f32 v32, v44, v45
	v_cvt_pk_bf16_f32 v33, v46, v47
	v_cvt_pk_bf16_f32 v34, v40, v41
	v_cvt_pk_bf16_f32 v35, v42, v43
	global_store_dwordx4 v147, v[32:35], s[8:9]
	s_waitcnt vmcnt(8)
	v_add_f32_e32 v204, v204, v205
	v_add_f32_e32 v206, v206, v207
	v_add_f32_e32 v208, v208, v209
	v_add_f32_e32 v210, v210, v211
	v_add_f32_e32 v204, v204, v206
	v_add_f32_e32 v208, v208, v210
	v_add_f32_e32 v204, v204, v208
	v_fmamk_f32 v254, v204, 0x3a000000, v154
	v_rsq_f32_e32 v146, v254
	v_add_u32_e32 v147, 0x1b8000, v155
	v_mul_f32_e32 v255, v146, v252
	v_pk_mul_f32 v[204:205], v[20:21], v[254:255] op_sel:[0,1]
	v_pk_mul_f32 v[206:207], v[22:23], v[254:255] op_sel:[0,1]
	v_pk_mul_f32 v[208:209], v[16:17], v[254:255] op_sel:[0,1]
	v_pk_mul_f32 v[210:211], v[18:19], v[254:255] op_sel:[0,1]
	v_exp_f32_e32 v204, v204
	v_exp_f32_e32 v205, v205
	v_exp_f32_e32 v206, v206
	v_exp_f32_e32 v207, v207
	v_exp_f32_e32 v208, v208
	v_exp_f32_e32 v209, v209
	v_exp_f32_e32 v210, v210
	v_exp_f32_e32 v211, v211
	v_pk_fma_f32 v[204:205], v[204:205], v[254:255], v[254:255] op_sel_hi:[1,0,0]
	v_pk_fma_f32 v[206:207], v[206:207], v[254:255], v[254:255] op_sel_hi:[1,0,0]
	v_pk_fma_f32 v[208:209], v[208:209], v[254:255], v[254:255] op_sel_hi:[1,0,0]
	v_pk_fma_f32 v[210:211], v[210:211], v[254:255], v[254:255] op_sel_hi:[1,0,0]
	v_rcp_f32_e32 v204, v204
	v_rcp_f32_e32 v205, v205
	v_rcp_f32_e32 v206, v206
	v_rcp_f32_e32 v207, v207
	v_rcp_f32_e32 v208, v208
	v_rcp_f32_e32 v209, v209
	v_rcp_f32_e32 v210, v210
	v_rcp_f32_e32 v211, v211
	v_pk_mul_f32 v[28:29], v[28:29], v[204:205]
	v_pk_mul_f32 v[30:31], v[30:31], v[206:207]
	v_pk_mul_f32 v[24:25], v[24:25], v[208:209]
	v_pk_mul_f32 v[26:27], v[26:27], v[210:211]
	v_cvt_pk_bf16_f32 v16, v28, v29
	v_cvt_pk_bf16_f32 v17, v30, v31
	v_cvt_pk_bf16_f32 v18, v24, v25
	v_cvt_pk_bf16_f32 v19, v26, v27
	global_store_dwordx4 v147, v[16:19], s[8:9]
	s_waitcnt vmcnt(7)
	v_add_f32_e32 v212, v212, v213
	v_add_f32_e32 v214, v214, v215
	v_add_f32_e32 v216, v216, v217
	v_add_f32_e32 v218, v218, v219
	v_add_f32_e32 v212, v212, v214
	v_add_f32_e32 v216, v216, v218
	v_add_f32_e32 v212, v212, v216
	v_fmamk_f32 v254, v212, 0x3a000000, v154
	v_rsq_f32_e32 v146, v254
	v_add_u32_e32 v147, 0x1e4000, v155
	v_mul_f32_e32 v255, v146, v252
	v_pk_mul_f32 v[212:213], v[8:9], v[254:255] op_sel:[0,1]
	v_pk_mul_f32 v[214:215], v[10:11], v[254:255] op_sel:[0,1]
	v_pk_mul_f32 v[216:217], v[0:1], v[254:255] op_sel:[0,1]
	v_pk_mul_f32 v[218:219], v[2:3], v[254:255] op_sel:[0,1]
	v_exp_f32_e32 v212, v212
	v_exp_f32_e32 v213, v213
	v_exp_f32_e32 v214, v214
	v_exp_f32_e32 v215, v215
	v_exp_f32_e32 v216, v216
	v_exp_f32_e32 v217, v217
	v_exp_f32_e32 v218, v218
	v_exp_f32_e32 v219, v219
	v_pk_fma_f32 v[212:213], v[212:213], v[254:255], v[254:255] op_sel_hi:[1,0,0]
	v_pk_fma_f32 v[214:215], v[214:215], v[254:255], v[254:255] op_sel_hi:[1,0,0]
	v_pk_fma_f32 v[216:217], v[216:217], v[254:255], v[254:255] op_sel_hi:[1,0,0]
	v_pk_fma_f32 v[218:219], v[218:219], v[254:255], v[254:255] op_sel_hi:[1,0,0]
	v_rcp_f32_e32 v212, v212
	v_rcp_f32_e32 v213, v213
	v_rcp_f32_e32 v214, v214
	v_rcp_f32_e32 v215, v215
	v_rcp_f32_e32 v216, v216
	v_rcp_f32_e32 v217, v217
	v_rcp_f32_e32 v218, v218
	v_rcp_f32_e32 v219, v219
	v_pk_mul_f32 v[12:13], v[12:13], v[212:213]
	v_pk_mul_f32 v[14:15], v[14:15], v[214:215]
	v_pk_mul_f32 v[4:5], v[4:5], v[216:217]
	v_pk_mul_f32 v[6:7], v[6:7], v[218:219]
	v_cvt_pk_bf16_f32 v0, v12, v13
	v_cvt_pk_bf16_f32 v1, v14, v15
	v_cvt_pk_bf16_f32 v2, v4, v5
	v_cvt_pk_bf16_f32 v3, v6, v7
	global_store_dwordx4 v147, v[0:3], s[8:9]
	s_cbranch_vccnz .LBB0_667
	s_andn2_b64 vcc, exec, s[6:7]
	s_cbranch_vccnz .LBB0_666
	s_barrier
	s_branch .LBB0_666
